# hand-written gate scan with batched loads + batched convert_c0 loads, on top of v14
# speedup vs baseline: 1.0108x; 1.0108x over previous
.LBB0_457:
	s_mov_b64 s[88:89], 0x18000
	s_or_b64 exec, exec, s[0:1]
	s_mov_b64 s[4:5], s[86:87]
	s_waitcnt lgkmcnt(0)
	s_barrier
	s_load_dwordx2 s[14:15], s[4:5], 0x28
	s_load_dwordx4 s[52:55], s[4:5], 0x98
	s_mov_b32 s0, s84
	v_mov_b32_e32 v0, v244
	s_nop 0
	v_lshl_add_u32 v0, s0, 8, v0
	s_mov_b32 s0, 0x100000
	v_cmp_gt_i32_e32 vcc, s0, v0
	s_and_saveexec_b64 s[0:1], vcc
	s_cbranch_execz .LBB0_460
	s_load_dwordx2 s[4:5], s[4:5], 0x18
	s_waitcnt lgkmcnt(0)
	s_add_u32 s6, s54, 0x22bd8000
	s_addc_u32 s7, s55, 0
	s_mov_b64 s[8:9], 0
	s_load_dword s2, s[90:91], 0x0
	s_waitcnt lgkmcnt(0)
	s_cmpk_lg_i32 s2, 0x200
	s_cbranch_scc1 .LBB0_459
	v_mov_b32_e32 v11, v0
	v_ashrrev_i32_e32 v4, 15, v11
	v_ashrrev_i32_e32 v10, 14, v11
	v_and_b32_e32 v4, 0xffffc, v4
	v_lshrrev_b32_e32 v5, 14, v11
	v_and_b32_e32 v3, 3, v10
	v_add_lshl_u32 v4, v4, s46, 3
	v_and_b32_e32 v5, 4, v5
	v_bfe_u32 v2, v11, 5, 9
	v_or3_b32 v3, v4, v5, v3
	v_lshl_or_b32 v2, v3, 9, v2
	v_ashrrev_i32_e32 v3, 31, v2
	v_and_b32_e32 v1, 31, v11
	v_lshlrev_b64 v[2:3], 10, v[2:3]
	v_lshl_add_u64 v[2:3], s[4:5], 0, v[2:3]
	v_lshlrev_b32_e32 v4, 5, v1
	v_mov_b32_e32 v5, v96
	v_lshl_add_u64 v[6:7], v[2:3], 0, v[4:5]
	global_load_dwordx4 v[104:107], v[6:7], off offset:16
	global_load_dwordx4 v[100:103], v[6:7], off
	v_add_u32_e32 v11, 0x20000, v0
	v_ashrrev_i32_e32 v4, 15, v11
	v_ashrrev_i32_e32 v10, 14, v11
	v_and_b32_e32 v4, 0xffffc, v4
	v_lshrrev_b32_e32 v5, 14, v11
	v_and_b32_e32 v3, 3, v10
	v_add_lshl_u32 v4, v4, s46, 3
	v_and_b32_e32 v5, 4, v5
	v_bfe_u32 v2, v11, 5, 9
	v_or3_b32 v3, v4, v5, v3
	v_lshl_or_b32 v2, v3, 9, v2
	v_ashrrev_i32_e32 v3, 31, v2
	v_and_b32_e32 v1, 31, v11
	v_lshlrev_b64 v[2:3], 10, v[2:3]
	v_lshl_add_u64 v[2:3], s[4:5], 0, v[2:3]
	v_lshlrev_b32_e32 v4, 5, v1
	v_mov_b32_e32 v5, v96
	v_lshl_add_u64 v[6:7], v[2:3], 0, v[4:5]
	global_load_dwordx4 v[112:115], v[6:7], off offset:16
	global_load_dwordx4 v[108:111], v[6:7], off
	v_add_u32_e32 v11, 0x40000, v0
	v_ashrrev_i32_e32 v4, 15, v11
	v_ashrrev_i32_e32 v10, 14, v11
	v_and_b32_e32 v4, 0xffffc, v4
	v_lshrrev_b32_e32 v5, 14, v11
	v_and_b32_e32 v3, 3, v10
	v_add_lshl_u32 v4, v4, s46, 3
	v_and_b32_e32 v5, 4, v5
	v_bfe_u32 v2, v11, 5, 9
	v_or3_b32 v3, v4, v5, v3
	v_lshl_or_b32 v2, v3, 9, v2
	v_ashrrev_i32_e32 v3, 31, v2
	v_and_b32_e32 v1, 31, v11
	v_lshlrev_b64 v[2:3], 10, v[2:3]
	v_lshl_add_u64 v[2:3], s[4:5], 0, v[2:3]
	v_lshlrev_b32_e32 v4, 5, v1
	v_mov_b32_e32 v5, v96
	v_lshl_add_u64 v[6:7], v[2:3], 0, v[4:5]
	global_load_dwordx4 v[120:123], v[6:7], off offset:16
	global_load_dwordx4 v[116:119], v[6:7], off
	v_add_u32_e32 v11, 0x60000, v0
	v_ashrrev_i32_e32 v4, 15, v11
	v_ashrrev_i32_e32 v10, 14, v11
	v_and_b32_e32 v4, 0xffffc, v4
	v_lshrrev_b32_e32 v5, 14, v11
	v_and_b32_e32 v3, 3, v10
	v_add_lshl_u32 v4, v4, s46, 3
	v_and_b32_e32 v5, 4, v5
	v_bfe_u32 v2, v11, 5, 9
	v_or3_b32 v3, v4, v5, v3
	v_lshl_or_b32 v2, v3, 9, v2
	v_ashrrev_i32_e32 v3, 31, v2
	v_and_b32_e32 v1, 31, v11
	v_lshlrev_b64 v[2:3], 10, v[2:3]
	v_lshl_add_u64 v[2:3], s[4:5], 0, v[2:3]
	v_lshlrev_b32_e32 v4, 5, v1
	v_mov_b32_e32 v5, v96
	v_lshl_add_u64 v[6:7], v[2:3], 0, v[4:5]
	global_load_dwordx4 v[128:131], v[6:7], off offset:16
	global_load_dwordx4 v[124:127], v[6:7], off
	v_add_u32_e32 v11, 0x80000, v0
	v_ashrrev_i32_e32 v4, 15, v11
	v_ashrrev_i32_e32 v10, 14, v11
	v_and_b32_e32 v4, 0xffffc, v4
	v_lshrrev_b32_e32 v5, 14, v11
	v_and_b32_e32 v3, 3, v10
	v_add_lshl_u32 v4, v4, s46, 3
	v_and_b32_e32 v5, 4, v5
	v_bfe_u32 v2, v11, 5, 9
	v_or3_b32 v3, v4, v5, v3
	v_lshl_or_b32 v2, v3, 9, v2
	v_ashrrev_i32_e32 v3, 31, v2
	v_and_b32_e32 v1, 31, v11
	v_lshlrev_b64 v[2:3], 10, v[2:3]
	v_lshl_add_u64 v[2:3], s[4:5], 0, v[2:3]
	v_lshlrev_b32_e32 v4, 5, v1
	v_mov_b32_e32 v5, v96
	v_lshl_add_u64 v[6:7], v[2:3], 0, v[4:5]
	global_load_dwordx4 v[136:139], v[6:7], off offset:16
	global_load_dwordx4 v[132:135], v[6:7], off
	v_add_u32_e32 v11, 0xa0000, v0
	v_ashrrev_i32_e32 v4, 15, v11
	v_ashrrev_i32_e32 v10, 14, v11
	v_and_b32_e32 v4, 0xffffc, v4
	v_lshrrev_b32_e32 v5, 14, v11
	v_and_b32_e32 v3, 3, v10
	v_add_lshl_u32 v4, v4, s46, 3
	v_and_b32_e32 v5, 4, v5
	v_bfe_u32 v2, v11, 5, 9
	v_or3_b32 v3, v4, v5, v3
	v_lshl_or_b32 v2, v3, 9, v2
	v_ashrrev_i32_e32 v3, 31, v2
	v_and_b32_e32 v1, 31, v11
	v_lshlrev_b64 v[2:3], 10, v[2:3]
	v_lshl_add_u64 v[2:3], s[4:5], 0, v[2:3]
	v_lshlrev_b32_e32 v4, 5, v1
	v_mov_b32_e32 v5, v96
	v_lshl_add_u64 v[6:7], v[2:3], 0, v[4:5]
	global_load_dwordx4 v[144:147], v[6:7], off offset:16
	global_load_dwordx4 v[140:143], v[6:7], off
	v_add_u32_e32 v11, 0xc0000, v0
	v_ashrrev_i32_e32 v4, 15, v11
	v_ashrrev_i32_e32 v10, 14, v11
	v_and_b32_e32 v4, 0xffffc, v4
	v_lshrrev_b32_e32 v5, 14, v11
	v_and_b32_e32 v3, 3, v10
	v_add_lshl_u32 v4, v4, s46, 3
	v_and_b32_e32 v5, 4, v5
	v_bfe_u32 v2, v11, 5, 9
	v_or3_b32 v3, v4, v5, v3
	v_lshl_or_b32 v2, v3, 9, v2
	v_ashrrev_i32_e32 v3, 31, v2
	v_and_b32_e32 v1, 31, v11
	v_lshlrev_b64 v[2:3], 10, v[2:3]
	v_lshl_add_u64 v[2:3], s[4:5], 0, v[2:3]
	v_lshlrev_b32_e32 v4, 5, v1
	v_mov_b32_e32 v5, v96
	v_lshl_add_u64 v[6:7], v[2:3], 0, v[4:5]
	global_load_dwordx4 v[152:155], v[6:7], off offset:16
	global_load_dwordx4 v[148:151], v[6:7], off
	v_add_u32_e32 v11, 0xe0000, v0
	v_ashrrev_i32_e32 v4, 15, v11
	v_ashrrev_i32_e32 v10, 14, v11
	v_and_b32_e32 v4, 0xffffc, v4
	v_lshrrev_b32_e32 v5, 14, v11
	v_and_b32_e32 v3, 3, v10
	v_add_lshl_u32 v4, v4, s46, 3
	v_and_b32_e32 v5, 4, v5
	v_bfe_u32 v2, v11, 5, 9
	v_or3_b32 v3, v4, v5, v3
	v_lshl_or_b32 v2, v3, 9, v2
	v_ashrrev_i32_e32 v3, 31, v2
	v_and_b32_e32 v1, 31, v11
	v_lshlrev_b64 v[2:3], 10, v[2:3]
	v_lshl_add_u64 v[2:3], s[4:5], 0, v[2:3]
	v_lshlrev_b32_e32 v4, 5, v1
	v_mov_b32_e32 v5, v96
	v_lshl_add_u64 v[6:7], v[2:3], 0, v[4:5]
	global_load_dwordx4 v[160:163], v[6:7], off offset:16
	global_load_dwordx4 v[156:159], v[6:7], off
	s_waitcnt vmcnt(0)
	v_mov_b32_e32 v11, v0
	v_ashrrev_i32_e32 v10, 14, v11
	v_lshlrev_b32_e32 v1, 4, v10
	v_lshrrev_b32_e32 v2, 10, v11
	v_and_b32_e32 v2, 8, v2
	v_bfe_u32 v3, v11, 2, 3
	v_or3_b32 v2, v1, v2, v3
	v_ashrrev_i32_e32 v3, 31, v2
	v_and_b32_e32 v1, 0x1fe0, v11
	v_lshlrev_b64 v[2:3], 14, v[2:3]
	v_lshl_add_u64 v[2:3], s[6:7], 0, v[2:3]
	v_lshlrev_b32_e32 v4, 1, v1
	v_mov_b32_e32 v5, v96
	v_lshlrev_b32_e32 v1, 4, v11
	v_lshl_add_u64 v[2:3], v[2:3], 0, v[4:5]
	v_and_b32_e32 v4, 48, v1
	v_lshl_add_u64 v[2:3], v[2:3], 0, v[4:5]
	v_cvt_pk_bf16_f32 v6, v100, v101
	v_cvt_pk_bf16_f32 v7, v102, v103
	v_cvt_pk_bf16_f32 v8, v104, v105
	v_cvt_pk_bf16_f32 v9, v106, v107
	global_store_dwordx4 v[2:3], v[6:9], off
	v_add_u32_e32 v11, 0x20000, v0
	v_ashrrev_i32_e32 v10, 14, v11
	v_lshlrev_b32_e32 v1, 4, v10
	v_lshrrev_b32_e32 v2, 10, v11
	v_and_b32_e32 v2, 8, v2
	v_bfe_u32 v3, v11, 2, 3
	v_or3_b32 v2, v1, v2, v3
	v_ashrrev_i32_e32 v3, 31, v2
	v_and_b32_e32 v1, 0x1fe0, v11
	v_lshlrev_b64 v[2:3], 14, v[2:3]
	v_lshl_add_u64 v[2:3], s[6:7], 0, v[2:3]
	v_lshlrev_b32_e32 v4, 1, v1
	v_mov_b32_e32 v5, v96
	v_lshlrev_b32_e32 v1, 4, v11
	v_lshl_add_u64 v[2:3], v[2:3], 0, v[4:5]
	v_and_b32_e32 v4, 48, v1
	v_lshl_add_u64 v[2:3], v[2:3], 0, v[4:5]
	v_cvt_pk_bf16_f32 v6, v108, v109
	v_cvt_pk_bf16_f32 v7, v110, v111
	v_cvt_pk_bf16_f32 v8, v112, v113
	v_cvt_pk_bf16_f32 v9, v114, v115
	global_store_dwordx4 v[2:3], v[6:9], off
	v_add_u32_e32 v11, 0x40000, v0
	v_ashrrev_i32_e32 v10, 14, v11
	v_lshlrev_b32_e32 v1, 4, v10
	v_lshrrev_b32_e32 v2, 10, v11
	v_and_b32_e32 v2, 8, v2
	v_bfe_u32 v3, v11, 2, 3
	v_or3_b32 v2, v1, v2, v3
	v_ashrrev_i32_e32 v3, 31, v2
	v_and_b32_e32 v1, 0x1fe0, v11
	v_lshlrev_b64 v[2:3], 14, v[2:3]
	v_lshl_add_u64 v[2:3], s[6:7], 0, v[2:3]
	v_lshlrev_b32_e32 v4, 1, v1
	v_mov_b32_e32 v5, v96
	v_lshlrev_b32_e32 v1, 4, v11
	v_lshl_add_u64 v[2:3], v[2:3], 0, v[4:5]
	v_and_b32_e32 v4, 48, v1
	v_lshl_add_u64 v[2:3], v[2:3], 0, v[4:5]
	v_cvt_pk_bf16_f32 v6, v116, v117
	v_cvt_pk_bf16_f32 v7, v118, v119
	v_cvt_pk_bf16_f32 v8, v120, v121
	v_cvt_pk_bf16_f32 v9, v122, v123
	global_store_dwordx4 v[2:3], v[6:9], off
	v_add_u32_e32 v11, 0x60000, v0
	v_ashrrev_i32_e32 v10, 14, v11
	v_lshlrev_b32_e32 v1, 4, v10
	v_lshrrev_b32_e32 v2, 10, v11
	v_and_b32_e32 v2, 8, v2
	v_bfe_u32 v3, v11, 2, 3
	v_or3_b32 v2, v1, v2, v3
	v_ashrrev_i32_e32 v3, 31, v2
	v_and_b32_e32 v1, 0x1fe0, v11
	v_lshlrev_b64 v[2:3], 14, v[2:3]
	v_lshl_add_u64 v[2:3], s[6:7], 0, v[2:3]
	v_lshlrev_b32_e32 v4, 1, v1
	v_mov_b32_e32 v5, v96
	v_lshlrev_b32_e32 v1, 4, v11
	v_lshl_add_u64 v[2:3], v[2:3], 0, v[4:5]
	v_and_b32_e32 v4, 48, v1
	v_lshl_add_u64 v[2:3], v[2:3], 0, v[4:5]
	v_cvt_pk_bf16_f32 v6, v124, v125
	v_cvt_pk_bf16_f32 v7, v126, v127
	v_cvt_pk_bf16_f32 v8, v128, v129
	v_cvt_pk_bf16_f32 v9, v130, v131
	global_store_dwordx4 v[2:3], v[6:9], off
	v_add_u32_e32 v11, 0x80000, v0
	v_ashrrev_i32_e32 v10, 14, v11
	v_lshlrev_b32_e32 v1, 4, v10
	v_lshrrev_b32_e32 v2, 10, v11
	v_and_b32_e32 v2, 8, v2
	v_bfe_u32 v3, v11, 2, 3
	v_or3_b32 v2, v1, v2, v3
	v_ashrrev_i32_e32 v3, 31, v2
	v_and_b32_e32 v1, 0x1fe0, v11
	v_lshlrev_b64 v[2:3], 14, v[2:3]
	v_lshl_add_u64 v[2:3], s[6:7], 0, v[2:3]
	v_lshlrev_b32_e32 v4, 1, v1
	v_mov_b32_e32 v5, v96
	v_lshlrev_b32_e32 v1, 4, v11
	v_lshl_add_u64 v[2:3], v[2:3], 0, v[4:5]
	v_and_b32_e32 v4, 48, v1
	v_lshl_add_u64 v[2:3], v[2:3], 0, v[4:5]
	v_cvt_pk_bf16_f32 v6, v132, v133
	v_cvt_pk_bf16_f32 v7, v134, v135
	v_cvt_pk_bf16_f32 v8, v136, v137
	v_cvt_pk_bf16_f32 v9, v138, v139
	global_store_dwordx4 v[2:3], v[6:9], off
	v_add_u32_e32 v11, 0xa0000, v0
	v_ashrrev_i32_e32 v10, 14, v11
	v_lshlrev_b32_e32 v1, 4, v10
	v_lshrrev_b32_e32 v2, 10, v11
	v_and_b32_e32 v2, 8, v2
	v_bfe_u32 v3, v11, 2, 3
	v_or3_b32 v2, v1, v2, v3
	v_ashrrev_i32_e32 v3, 31, v2
	v_and_b32_e32 v1, 0x1fe0, v11
	v_lshlrev_b64 v[2:3], 14, v[2:3]
	v_lshl_add_u64 v[2:3], s[6:7], 0, v[2:3]
	v_lshlrev_b32_e32 v4, 1, v1
	v_mov_b32_e32 v5, v96
	v_lshlrev_b32_e32 v1, 4, v11
	v_lshl_add_u64 v[2:3], v[2:3], 0, v[4:5]
	v_and_b32_e32 v4, 48, v1
	v_lshl_add_u64 v[2:3], v[2:3], 0, v[4:5]
	v_cvt_pk_bf16_f32 v6, v140, v141
	v_cvt_pk_bf16_f32 v7, v142, v143
	v_cvt_pk_bf16_f32 v8, v144, v145
	v_cvt_pk_bf16_f32 v9, v146, v147
	global_store_dwordx4 v[2:3], v[6:9], off
	v_add_u32_e32 v11, 0xc0000, v0
	v_ashrrev_i32_e32 v10, 14, v11
	v_lshlrev_b32_e32 v1, 4, v10
	v_lshrrev_b32_e32 v2, 10, v11
	v_and_b32_e32 v2, 8, v2
	v_bfe_u32 v3, v11, 2, 3
	v_or3_b32 v2, v1, v2, v3
	v_ashrrev_i32_e32 v3, 31, v2
	v_and_b32_e32 v1, 0x1fe0, v11
	v_lshlrev_b64 v[2:3], 14, v[2:3]
	v_lshl_add_u64 v[2:3], s[6:7], 0, v[2:3]
	v_lshlrev_b32_e32 v4, 1, v1
	v_mov_b32_e32 v5, v96
	v_lshlrev_b32_e32 v1, 4, v11
	v_lshl_add_u64 v[2:3], v[2:3], 0, v[4:5]
	v_and_b32_e32 v4, 48, v1
	v_lshl_add_u64 v[2:3], v[2:3], 0, v[4:5]
	v_cvt_pk_bf16_f32 v6, v148, v149
	v_cvt_pk_bf16_f32 v7, v150, v151
	v_cvt_pk_bf16_f32 v8, v152, v153
	v_cvt_pk_bf16_f32 v9, v154, v155
	global_store_dwordx4 v[2:3], v[6:9], off
	v_add_u32_e32 v11, 0xe0000, v0
	v_ashrrev_i32_e32 v10, 14, v11
	v_lshlrev_b32_e32 v1, 4, v10
	v_lshrrev_b32_e32 v2, 10, v11
	v_and_b32_e32 v2, 8, v2
	v_bfe_u32 v3, v11, 2, 3
	v_or3_b32 v2, v1, v2, v3
	v_ashrrev_i32_e32 v3, 31, v2
	v_and_b32_e32 v1, 0x1fe0, v11
	v_lshlrev_b64 v[2:3], 14, v[2:3]
	v_lshl_add_u64 v[2:3], s[6:7], 0, v[2:3]
	v_lshlrev_b32_e32 v4, 1, v1
	v_mov_b32_e32 v5, v96
	v_lshlrev_b32_e32 v1, 4, v11
	v_lshl_add_u64 v[2:3], v[2:3], 0, v[4:5]
	v_and_b32_e32 v4, 48, v1
	v_lshl_add_u64 v[2:3], v[2:3], 0, v[4:5]
	v_cvt_pk_bf16_f32 v6, v156, v157
	v_cvt_pk_bf16_f32 v7, v158, v159
	v_cvt_pk_bf16_f32 v8, v160, v161
	v_cvt_pk_bf16_f32 v9, v162, v163
	global_store_dwordx4 v[2:3], v[6:9], off
	s_branch .LBB0_460

.LBB0_531:
	s_and_b64 vcc, exec, s[0:1]
	s_cbranch_vccz .LBB0_464
	v_lshrrev_b32_e32 v0, 6, v244
	v_and_b32_e32 v1, 63, v244
	v_readlane_b32 s8, v255, 8
	v_readfirstlane_b32 s0, v0
	s_lshl_b32 s1, s2, 2
	s_add_i32 s1, s1, s0
	s_and_b32 s4, s1, 1
	s_bfe_u32 s5, s1, 0x20001
	s_lshr_b32 s6, s1, 3
	s_lshl_b32 s9, s4, 2
	s_add_i32 s9, s9, s5
	s_mul_i32 s10, s9, 0xc000
	s_lshl_b32 s11, s4, 5
	s_lshl_b32 s9, s5, 2
	s_add_i32 s11, s11, s9
	s_cmp_lt_i32 s2, 32
	s_cbranch_scc0 .Lscan_e16
	s_lshl_b32 s7, s6, 8
	s_cmp_eq_u32 s4, 0
	s_cbranch_scc0 .Lscan_e4_d1
	v_mul_u32_u24_e32 v0, 4, v1
	v_add_u32_e32 v0, s7, v0
	v_lshlrev_b32_e32 v2, 6, v0
	v_add_u32_e32 v2, s11, v2
	v_lshlrev_b32_e32 v3, 2, v0
	v_add_u32_e32 v3, s10, v3
	global_load_dword v4, v2, s[20:21] offset:16
	global_load_dword v20, v2, s[20:21] offset:0
	global_load_dword v5, v2, s[20:21] offset:80
	global_load_dword v21, v2, s[20:21] offset:64
	global_load_dword v6, v2, s[20:21] offset:144
	global_load_dword v22, v2, s[20:21] offset:128
	global_load_dword v7, v2, s[20:21] offset:208
	global_load_dword v23, v2, s[20:21] offset:192
	s_waitcnt vmcnt(0) lgkmcnt(0)
	v_add_f32_e32 v39, 0, v4
	v_add_f32_e32 v39, v39, v5
	v_add_f32_e32 v39, v39, v6
	v_add_f32_e32 v39, v39, v7
	v_mov_b32_e32 v36, v39
	v_subrev_u32_e32 v38, 1, v1
	v_lshlrev_b32_e32 v38, 2, v38
	ds_bpermute_b32 v37, v38, v36
	v_cmp_le_u32_e32 vcc, 1, v1
	s_waitcnt lgkmcnt(0)
	v_add_f32_e32 v37, v36, v37
	s_nop 0
	v_cndmask_b32_e32 v36, v36, v37, vcc
	v_subrev_u32_e32 v38, 2, v1
	v_lshlrev_b32_e32 v38, 2, v38
	ds_bpermute_b32 v37, v38, v36
	v_cmp_le_u32_e32 vcc, 2, v1
	s_waitcnt lgkmcnt(0)
	v_add_f32_e32 v37, v36, v37
	s_nop 0
	v_cndmask_b32_e32 v36, v36, v37, vcc
	v_subrev_u32_e32 v38, 4, v1
	v_lshlrev_b32_e32 v38, 2, v38
	ds_bpermute_b32 v37, v38, v36
	v_cmp_le_u32_e32 vcc, 4, v1
	s_waitcnt lgkmcnt(0)
	v_add_f32_e32 v37, v36, v37
	s_nop 0
	v_cndmask_b32_e32 v36, v36, v37, vcc
	v_subrev_u32_e32 v38, 8, v1
	v_lshlrev_b32_e32 v38, 2, v38
	ds_bpermute_b32 v37, v38, v36
	v_cmp_le_u32_e32 vcc, 8, v1
	s_waitcnt lgkmcnt(0)
	v_add_f32_e32 v37, v36, v37
	s_nop 0
	v_cndmask_b32_e32 v36, v36, v37, vcc
	v_subrev_u32_e32 v38, 16, v1
	v_lshlrev_b32_e32 v38, 2, v38
	ds_bpermute_b32 v37, v38, v36
	v_cmp_le_u32_e32 vcc, 16, v1
	s_waitcnt lgkmcnt(0)
	v_add_f32_e32 v37, v36, v37
	s_nop 0
	v_cndmask_b32_e32 v36, v36, v37, vcc
	v_subrev_u32_e32 v38, 32, v1
	v_lshlrev_b32_e32 v38, 2, v38
	ds_bpermute_b32 v37, v38, v36
	v_cmp_le_u32_e32 vcc, 32, v1
	s_waitcnt lgkmcnt(0)
	v_add_f32_e32 v37, v36, v37
	s_nop 0
	v_cndmask_b32_e32 v36, v36, v37, vcc
	v_sub_f32_e32 v40, v36, v39
	v_mov_b32_e32 v41, 0xff61b1e6
	v_add_f32_e32 v4, v40, v4
	v_sub_f32_e32 v20, v20, v4
	global_store_dword v3, v20, s[42:43] offset:0
	v_max_f32_e32 v41, v41, v20
	v_add_f32_e32 v5, v4, v5
	v_sub_f32_e32 v21, v21, v5
	global_store_dword v3, v21, s[42:43] offset:4
	v_max_f32_e32 v41, v41, v21
	v_add_f32_e32 v6, v5, v6
	v_sub_f32_e32 v22, v22, v6
	global_store_dword v3, v22, s[42:43] offset:8
	v_max_f32_e32 v41, v41, v22
	v_add_f32_e32 v7, v6, v7
	v_sub_f32_e32 v23, v23, v7
	global_store_dword v3, v23, s[42:43] offset:12
	v_max_f32_e32 v41, v41, v23
	v_mov_b32_e32 v36, v41
	v_subrev_u32_e32 v38, 1, v1
	v_lshlrev_b32_e32 v38, 2, v38
	ds_bpermute_b32 v37, v38, v36
	v_cmp_le_u32_e32 vcc, 1, v1
	s_waitcnt lgkmcnt(0)
	v_max_f32_e32 v37, v36, v37
	s_nop 0
	v_cndmask_b32_e32 v36, v36, v37, vcc
	v_subrev_u32_e32 v38, 2, v1
	v_lshlrev_b32_e32 v38, 2, v38
	ds_bpermute_b32 v37, v38, v36
	v_cmp_le_u32_e32 vcc, 2, v1
	s_waitcnt lgkmcnt(0)
	v_max_f32_e32 v37, v36, v37
	s_nop 0
	v_cndmask_b32_e32 v36, v36, v37, vcc
	v_subrev_u32_e32 v38, 4, v1
	v_lshlrev_b32_e32 v38, 2, v38
	ds_bpermute_b32 v37, v38, v36
	v_cmp_le_u32_e32 vcc, 4, v1
	s_waitcnt lgkmcnt(0)
	v_max_f32_e32 v37, v36, v37
	s_nop 0
	v_cndmask_b32_e32 v36, v36, v37, vcc
	v_subrev_u32_e32 v38, 8, v1
	v_lshlrev_b32_e32 v38, 2, v38
	ds_bpermute_b32 v37, v38, v36
	v_cmp_le_u32_e32 vcc, 8, v1
	s_waitcnt lgkmcnt(0)
	v_max_f32_e32 v37, v36, v37
	s_nop 0
	v_cndmask_b32_e32 v36, v36, v37, vcc
	v_subrev_u32_e32 v38, 16, v1
	v_lshlrev_b32_e32 v38, 2, v38
	ds_bpermute_b32 v37, v38, v36
	v_cmp_le_u32_e32 vcc, 16, v1
	s_waitcnt lgkmcnt(0)
	v_max_f32_e32 v37, v36, v37
	s_nop 0
	v_cndmask_b32_e32 v36, v36, v37, vcc
	v_subrev_u32_e32 v38, 32, v1
	v_lshlrev_b32_e32 v38, 2, v38
	ds_bpermute_b32 v37, v38, v36
	v_cmp_le_u32_e32 vcc, 32, v1
	s_waitcnt lgkmcnt(0)
	v_max_f32_e32 v37, v36, v37
	s_nop 0
	v_cndmask_b32_e32 v36, v36, v37, vcc
	v_subrev_u32_e32 v38, 1, v1
	v_lshlrev_b32_e32 v38, 2, v38
	ds_bpermute_b32 v37, v38, v36
	v_mov_b32_e32 v42, 0
	v_cmp_eq_u32_e32 vcc, 0, v1
	s_waitcnt lgkmcnt(0)
	v_max_f32_e32 v37, v42, v37
	s_nop 0
	v_cndmask_b32_e32 v41, v37, v42, vcc
	v_max_f32_e32 v41, v41, v20
	global_store_dword v3, v41, s[44:45] offset:0
	v_sub_f32_e64 v43, -v4, v41
	v_mul_f32_e32 v43, 0x3fb8aa3b, v43
	v_exp_f32_e32 v43, v43
	s_nop 0
	global_store_dword v3, v43, s[46:47] offset:0
	v_max_f32_e32 v41, v41, v21
	global_store_dword v3, v41, s[44:45] offset:4
	v_sub_f32_e64 v43, -v5, v41
	v_mul_f32_e32 v43, 0x3fb8aa3b, v43
	v_exp_f32_e32 v43, v43
	s_nop 0
	global_store_dword v3, v43, s[46:47] offset:4
	v_max_f32_e32 v41, v41, v22
	global_store_dword v3, v41, s[44:45] offset:8
	v_sub_f32_e64 v43, -v6, v41
	v_mul_f32_e32 v43, 0x3fb8aa3b, v43
	v_exp_f32_e32 v43, v43
	s_nop 0
	global_store_dword v3, v43, s[46:47] offset:8
	v_max_f32_e32 v41, v41, v23
	global_store_dword v3, v41, s[44:45] offset:12
	v_sub_f32_e64 v43, -v7, v41
	v_mul_f32_e32 v43, 0x3fb8aa3b, v43
	v_exp_f32_e32 v43, v43
	s_nop 0
	global_store_dword v3, v43, s[46:47] offset:12
	s_nop 0
	v_readlane_b32 s0, v41, 63
	v_readlane_b32 s1, v7, 63
	s_lshl_b32 s9, s6, 2
	s_add_i32 s9, s9, s8
	s_lshl_b32 s9, s9, 1
	s_add_i32 s9, s9, s4
	s_lshl_b32 s9, s9, 2
	s_add_i32 s9, s9, s5
	s_lshl_b32 s9, s9, 2
	s_add_u32 s6, s52, 0x13080000
	s_addc_u32 s7, s53, 0
	s_add_u32 s6, s6, s9
	s_addc_u32 s7, s7, 0
	v_mov_b32_e32 v44, s0
	v_add_f32_e32 v45, s1, v44
	v_cmp_eq_u32_e32 vcc, 0, v1
	s_nop 1
	s_and_saveexec_b64 s[4:5], vcc
	global_store_dword v96, v45, s[6:7]
	s_mov_b64 exec, s[4:5]
	v_sub_f32_e32 v43, v20, v44
	v_mul_f32_e32 v43, 0x3fb8aa3b, v43
	v_exp_f32_e32 v43, v43
	s_nop 0
	global_store_dword v3, v43, s[16:17] offset:0
	v_sub_f32_e32 v43, v21, v44
	v_mul_f32_e32 v43, 0x3fb8aa3b, v43
	v_exp_f32_e32 v43, v43
	s_nop 0
	global_store_dword v3, v43, s[16:17] offset:4
	v_sub_f32_e32 v43, v22, v44
	v_mul_f32_e32 v43, 0x3fb8aa3b, v43
	v_exp_f32_e32 v43, v43
	s_nop 0
	global_store_dword v3, v43, s[16:17] offset:8
	v_sub_f32_e32 v43, v23, v44
	v_mul_f32_e32 v43, 0x3fb8aa3b, v43
	v_exp_f32_e32 v43, v43
	s_nop 0
	global_store_dword v3, v43, s[16:17] offset:12
	s_branch .LBB0_464
.Lscan_e4_d1:
	v_mul_u32_u24_e32 v0, 4, v1
	s_add_i32 s7, s7, 255
	v_sub_u32_e32 v0, s7, v0
	v_lshlrev_b32_e32 v2, 6, v0
	v_add_u32_e32 v2, s11, v2
	v_lshlrev_b32_e32 v3, 2, v0
	v_add_u32_e32 v3, s10, v3
	global_load_dword v4, v2, s[20:21] offset:16
	global_load_dword v20, v2, s[20:21] offset:0
	global_load_dword v5, v2, s[20:21] offset:-48
	global_load_dword v21, v2, s[20:21] offset:-64
	global_load_dword v6, v2, s[20:21] offset:-112
	global_load_dword v22, v2, s[20:21] offset:-128
	global_load_dword v7, v2, s[20:21] offset:-176
	global_load_dword v23, v2, s[20:21] offset:-192
	s_waitcnt vmcnt(0) lgkmcnt(0)
	v_add_f32_e32 v39, 0, v4
	v_add_f32_e32 v39, v39, v5
	v_add_f32_e32 v39, v39, v6
	v_add_f32_e32 v39, v39, v7
	v_mov_b32_e32 v36, v39
	v_subrev_u32_e32 v38, 1, v1
	v_lshlrev_b32_e32 v38, 2, v38
	ds_bpermute_b32 v37, v38, v36
	v_cmp_le_u32_e32 vcc, 1, v1
	s_waitcnt lgkmcnt(0)
	v_add_f32_e32 v37, v36, v37
	s_nop 0
	v_cndmask_b32_e32 v36, v36, v37, vcc
	v_subrev_u32_e32 v38, 2, v1
	v_lshlrev_b32_e32 v38, 2, v38
	ds_bpermute_b32 v37, v38, v36
	v_cmp_le_u32_e32 vcc, 2, v1
	s_waitcnt lgkmcnt(0)
	v_add_f32_e32 v37, v36, v37
	s_nop 0
	v_cndmask_b32_e32 v36, v36, v37, vcc
	v_subrev_u32_e32 v38, 4, v1
	v_lshlrev_b32_e32 v38, 2, v38
	ds_bpermute_b32 v37, v38, v36
	v_cmp_le_u32_e32 vcc, 4, v1
	s_waitcnt lgkmcnt(0)
	v_add_f32_e32 v37, v36, v37
	s_nop 0
	v_cndmask_b32_e32 v36, v36, v37, vcc
	v_subrev_u32_e32 v38, 8, v1
	v_lshlrev_b32_e32 v38, 2, v38
	ds_bpermute_b32 v37, v38, v36
	v_cmp_le_u32_e32 vcc, 8, v1
	s_waitcnt lgkmcnt(0)
	v_add_f32_e32 v37, v36, v37
	s_nop 0
	v_cndmask_b32_e32 v36, v36, v37, vcc
	v_subrev_u32_e32 v38, 16, v1
	v_lshlrev_b32_e32 v38, 2, v38
	ds_bpermute_b32 v37, v38, v36
	v_cmp_le_u32_e32 vcc, 16, v1
	s_waitcnt lgkmcnt(0)
	v_add_f32_e32 v37, v36, v37
	s_nop 0
	v_cndmask_b32_e32 v36, v36, v37, vcc
	v_subrev_u32_e32 v38, 32, v1
	v_lshlrev_b32_e32 v38, 2, v38
	ds_bpermute_b32 v37, v38, v36
	v_cmp_le_u32_e32 vcc, 32, v1
	s_waitcnt lgkmcnt(0)
	v_add_f32_e32 v37, v36, v37
	s_nop 0
	v_cndmask_b32_e32 v36, v36, v37, vcc
	v_sub_f32_e32 v40, v36, v39
	v_mov_b32_e32 v41, 0xff61b1e6
	v_add_f32_e32 v4, v40, v4
	v_sub_f32_e32 v20, v20, v4
	global_store_dword v3, v20, s[42:43] offset:0
	v_max_f32_e32 v41, v41, v20
	v_add_f32_e32 v5, v4, v5
	v_sub_f32_e32 v21, v21, v5
	global_store_dword v3, v21, s[42:43] offset:-4
	v_max_f32_e32 v41, v41, v21
	v_add_f32_e32 v6, v5, v6
	v_sub_f32_e32 v22, v22, v6
	global_store_dword v3, v22, s[42:43] offset:-8
	v_max_f32_e32 v41, v41, v22
	v_add_f32_e32 v7, v6, v7
	v_sub_f32_e32 v23, v23, v7
	global_store_dword v3, v23, s[42:43] offset:-12
	v_max_f32_e32 v41, v41, v23
	v_mov_b32_e32 v36, v41
	v_subrev_u32_e32 v38, 1, v1
	v_lshlrev_b32_e32 v38, 2, v38
	ds_bpermute_b32 v37, v38, v36
	v_cmp_le_u32_e32 vcc, 1, v1
	s_waitcnt lgkmcnt(0)
	v_max_f32_e32 v37, v36, v37
	s_nop 0
	v_cndmask_b32_e32 v36, v36, v37, vcc
	v_subrev_u32_e32 v38, 2, v1
	v_lshlrev_b32_e32 v38, 2, v38
	ds_bpermute_b32 v37, v38, v36
	v_cmp_le_u32_e32 vcc, 2, v1
	s_waitcnt lgkmcnt(0)
	v_max_f32_e32 v37, v36, v37
	s_nop 0
	v_cndmask_b32_e32 v36, v36, v37, vcc
	v_subrev_u32_e32 v38, 4, v1
	v_lshlrev_b32_e32 v38, 2, v38
	ds_bpermute_b32 v37, v38, v36
	v_cmp_le_u32_e32 vcc, 4, v1
	s_waitcnt lgkmcnt(0)
	v_max_f32_e32 v37, v36, v37
	s_nop 0
	v_cndmask_b32_e32 v36, v36, v37, vcc
	v_subrev_u32_e32 v38, 8, v1
	v_lshlrev_b32_e32 v38, 2, v38
	ds_bpermute_b32 v37, v38, v36
	v_cmp_le_u32_e32 vcc, 8, v1
	s_waitcnt lgkmcnt(0)
	v_max_f32_e32 v37, v36, v37
	s_nop 0
	v_cndmask_b32_e32 v36, v36, v37, vcc
	v_subrev_u32_e32 v38, 16, v1
	v_lshlrev_b32_e32 v38, 2, v38
	ds_bpermute_b32 v37, v38, v36
	v_cmp_le_u32_e32 vcc, 16, v1
	s_waitcnt lgkmcnt(0)
	v_max_f32_e32 v37, v36, v37
	s_nop 0
	v_cndmask_b32_e32 v36, v36, v37, vcc
	v_subrev_u32_e32 v38, 32, v1
	v_lshlrev_b32_e32 v38, 2, v38
	ds_bpermute_b32 v37, v38, v36
	v_cmp_le_u32_e32 vcc, 32, v1
	s_waitcnt lgkmcnt(0)
	v_max_f32_e32 v37, v36, v37
	s_nop 0
	v_cndmask_b32_e32 v36, v36, v37, vcc
	v_subrev_u32_e32 v38, 1, v1
	v_lshlrev_b32_e32 v38, 2, v38
	ds_bpermute_b32 v37, v38, v36
	v_mov_b32_e32 v42, 0
	v_cmp_eq_u32_e32 vcc, 0, v1
	s_waitcnt lgkmcnt(0)
	v_max_f32_e32 v37, v42, v37
	s_nop 0
	v_cndmask_b32_e32 v41, v37, v42, vcc
	v_max_f32_e32 v41, v41, v20
	global_store_dword v3, v41, s[44:45] offset:0
	v_sub_f32_e64 v43, -v4, v41
	v_mul_f32_e32 v43, 0x3fb8aa3b, v43
	v_exp_f32_e32 v43, v43
	s_nop 0
	global_store_dword v3, v43, s[46:47] offset:0
	v_max_f32_e32 v41, v41, v21
	global_store_dword v3, v41, s[44:45] offset:-4
	v_sub_f32_e64 v43, -v5, v41
	v_mul_f32_e32 v43, 0x3fb8aa3b, v43
	v_exp_f32_e32 v43, v43
	s_nop 0
	global_store_dword v3, v43, s[46:47] offset:-4
	v_max_f32_e32 v41, v41, v22
	global_store_dword v3, v41, s[44:45] offset:-8
	v_sub_f32_e64 v43, -v6, v41
	v_mul_f32_e32 v43, 0x3fb8aa3b, v43
	v_exp_f32_e32 v43, v43
	s_nop 0
	global_store_dword v3, v43, s[46:47] offset:-8
	v_max_f32_e32 v41, v41, v23
	global_store_dword v3, v41, s[44:45] offset:-12
	v_sub_f32_e64 v43, -v7, v41
	v_mul_f32_e32 v43, 0x3fb8aa3b, v43
	v_exp_f32_e32 v43, v43
	s_nop 0
	global_store_dword v3, v43, s[46:47] offset:-12
	s_nop 0
	v_readlane_b32 s0, v41, 63
	v_readlane_b32 s1, v7, 63
	s_lshl_b32 s9, s6, 2
	s_add_i32 s9, s9, s8
	s_lshl_b32 s9, s9, 1
	s_add_i32 s9, s9, s4
	s_lshl_b32 s9, s9, 2
	s_add_i32 s9, s9, s5
	s_lshl_b32 s9, s9, 2
	s_add_u32 s6, s52, 0x13080000
	s_addc_u32 s7, s53, 0
	s_add_u32 s6, s6, s9
	s_addc_u32 s7, s7, 0
	v_mov_b32_e32 v44, s0
	v_add_f32_e32 v45, s1, v44
	v_cmp_eq_u32_e32 vcc, 0, v1
	s_nop 1
	s_and_saveexec_b64 s[4:5], vcc
	global_store_dword v96, v45, s[6:7]
	s_mov_b64 exec, s[4:5]
	v_sub_f32_e32 v43, v20, v44
	v_mul_f32_e32 v43, 0x3fb8aa3b, v43
	v_exp_f32_e32 v43, v43
	s_nop 0
	global_store_dword v3, v43, s[16:17] offset:0
	v_sub_f32_e32 v43, v21, v44
	v_mul_f32_e32 v43, 0x3fb8aa3b, v43
	v_exp_f32_e32 v43, v43
	s_nop 0
	global_store_dword v3, v43, s[16:17] offset:-4
	v_sub_f32_e32 v43, v22, v44
	v_mul_f32_e32 v43, 0x3fb8aa3b, v43
	v_exp_f32_e32 v43, v43
	s_nop 0
	global_store_dword v3, v43, s[16:17] offset:-8
	v_sub_f32_e32 v43, v23, v44
	v_mul_f32_e32 v43, 0x3fb8aa3b, v43
	v_exp_f32_e32 v43, v43
	s_nop 0
	global_store_dword v3, v43, s[16:17] offset:-12
	s_branch .LBB0_464
.Lscan_e16:
	s_sub_i32 s7, s6, 16
	s_lshl_b32 s9, s7, 2
	s_add_i32 s9, s9, s8
	s_lshl_b32 s9, s9, 1
	s_add_i32 s9, s9, s4
	s_lshl_b32 s9, s9, 2
	s_add_i32 s9, s9, s5
	s_lshl_b32 s9, s9, 2
	s_load_dword s9, s[14:15], s9
	s_lshl_b32 s7, s7, 10
	s_addk_i32 s7, 0x1000
	s_cmp_eq_u32 s4, 0
	s_cbranch_scc0 .Lscan_e16_d1
	v_mul_u32_u24_e32 v0, 16, v1
	v_add_u32_e32 v0, s7, v0
	v_lshlrev_b32_e32 v2, 6, v0
	v_add_u32_e32 v2, s11, v2
	v_lshlrev_b32_e32 v3, 2, v0
	v_add_u32_e32 v3, s10, v3
	global_load_dword v4, v2, s[20:21] offset:16
	global_load_dword v20, v2, s[20:21] offset:0
	global_load_dword v5, v2, s[20:21] offset:80
	global_load_dword v21, v2, s[20:21] offset:64
	global_load_dword v6, v2, s[20:21] offset:144
	global_load_dword v22, v2, s[20:21] offset:128
	global_load_dword v7, v2, s[20:21] offset:208
	global_load_dword v23, v2, s[20:21] offset:192
	global_load_dword v8, v2, s[20:21] offset:272
	global_load_dword v24, v2, s[20:21] offset:256
	global_load_dword v9, v2, s[20:21] offset:336
	global_load_dword v25, v2, s[20:21] offset:320
	global_load_dword v10, v2, s[20:21] offset:400
	global_load_dword v26, v2, s[20:21] offset:384
	global_load_dword v11, v2, s[20:21] offset:464
	global_load_dword v27, v2, s[20:21] offset:448
	global_load_dword v12, v2, s[20:21] offset:528
	global_load_dword v28, v2, s[20:21] offset:512
	global_load_dword v13, v2, s[20:21] offset:592
	global_load_dword v29, v2, s[20:21] offset:576
	global_load_dword v14, v2, s[20:21] offset:656
	global_load_dword v30, v2, s[20:21] offset:640
	global_load_dword v15, v2, s[20:21] offset:720
	global_load_dword v31, v2, s[20:21] offset:704
	global_load_dword v16, v2, s[20:21] offset:784
	global_load_dword v32, v2, s[20:21] offset:768
	global_load_dword v17, v2, s[20:21] offset:848
	global_load_dword v33, v2, s[20:21] offset:832
	global_load_dword v18, v2, s[20:21] offset:912
	global_load_dword v34, v2, s[20:21] offset:896
	global_load_dword v19, v2, s[20:21] offset:976
	global_load_dword v35, v2, s[20:21] offset:960
	s_waitcnt vmcnt(0) lgkmcnt(0)
	v_add_f32_e32 v39, 0, v4
	v_add_f32_e32 v39, v39, v5
	v_add_f32_e32 v39, v39, v6
	v_add_f32_e32 v39, v39, v7
	v_add_f32_e32 v39, v39, v8
	v_add_f32_e32 v39, v39, v9
	v_add_f32_e32 v39, v39, v10
	v_add_f32_e32 v39, v39, v11
	v_add_f32_e32 v39, v39, v12
	v_add_f32_e32 v39, v39, v13
	v_add_f32_e32 v39, v39, v14
	v_add_f32_e32 v39, v39, v15
	v_add_f32_e32 v39, v39, v16
	v_add_f32_e32 v39, v39, v17
	v_add_f32_e32 v39, v39, v18
	v_add_f32_e32 v39, v39, v19
	v_mov_b32_e32 v36, v39
	v_subrev_u32_e32 v38, 1, v1
	v_lshlrev_b32_e32 v38, 2, v38
	ds_bpermute_b32 v37, v38, v36
	v_cmp_le_u32_e32 vcc, 1, v1
	s_waitcnt lgkmcnt(0)
	v_add_f32_e32 v37, v36, v37
	s_nop 0
	v_cndmask_b32_e32 v36, v36, v37, vcc
	v_subrev_u32_e32 v38, 2, v1
	v_lshlrev_b32_e32 v38, 2, v38
	ds_bpermute_b32 v37, v38, v36
	v_cmp_le_u32_e32 vcc, 2, v1
	s_waitcnt lgkmcnt(0)
	v_add_f32_e32 v37, v36, v37
	s_nop 0
	v_cndmask_b32_e32 v36, v36, v37, vcc
	v_subrev_u32_e32 v38, 4, v1
	v_lshlrev_b32_e32 v38, 2, v38
	ds_bpermute_b32 v37, v38, v36
	v_cmp_le_u32_e32 vcc, 4, v1
	s_waitcnt lgkmcnt(0)
	v_add_f32_e32 v37, v36, v37
	s_nop 0
	v_cndmask_b32_e32 v36, v36, v37, vcc
	v_subrev_u32_e32 v38, 8, v1
	v_lshlrev_b32_e32 v38, 2, v38
	ds_bpermute_b32 v37, v38, v36
	v_cmp_le_u32_e32 vcc, 8, v1
	s_waitcnt lgkmcnt(0)
	v_add_f32_e32 v37, v36, v37
	s_nop 0
	v_cndmask_b32_e32 v36, v36, v37, vcc
	v_subrev_u32_e32 v38, 16, v1
	v_lshlrev_b32_e32 v38, 2, v38
	ds_bpermute_b32 v37, v38, v36
	v_cmp_le_u32_e32 vcc, 16, v1
	s_waitcnt lgkmcnt(0)
	v_add_f32_e32 v37, v36, v37
	s_nop 0
	v_cndmask_b32_e32 v36, v36, v37, vcc
	v_subrev_u32_e32 v38, 32, v1
	v_lshlrev_b32_e32 v38, 2, v38
	ds_bpermute_b32 v37, v38, v36
	v_cmp_le_u32_e32 vcc, 32, v1
	s_waitcnt lgkmcnt(0)
	v_add_f32_e32 v37, v36, v37
	s_nop 0
	v_cndmask_b32_e32 v36, v36, v37, vcc
	v_sub_f32_e32 v40, v36, v39
	v_mov_b32_e32 v41, 0xff61b1e6
	v_add_f32_e32 v4, v40, v4
	v_sub_f32_e32 v20, v20, v4
	global_store_dword v3, v20, s[42:43] offset:0
	v_max_f32_e32 v41, v41, v20
	v_add_f32_e32 v5, v4, v5
	v_sub_f32_e32 v21, v21, v5
	global_store_dword v3, v21, s[42:43] offset:4
	v_max_f32_e32 v41, v41, v21
	v_add_f32_e32 v6, v5, v6
	v_sub_f32_e32 v22, v22, v6
	global_store_dword v3, v22, s[42:43] offset:8
	v_max_f32_e32 v41, v41, v22
	v_add_f32_e32 v7, v6, v7
	v_sub_f32_e32 v23, v23, v7
	global_store_dword v3, v23, s[42:43] offset:12
	v_max_f32_e32 v41, v41, v23
	v_add_f32_e32 v8, v7, v8
	v_sub_f32_e32 v24, v24, v8
	global_store_dword v3, v24, s[42:43] offset:16
	v_max_f32_e32 v41, v41, v24
	v_add_f32_e32 v9, v8, v9
	v_sub_f32_e32 v25, v25, v9
	global_store_dword v3, v25, s[42:43] offset:20
	v_max_f32_e32 v41, v41, v25
	v_add_f32_e32 v10, v9, v10
	v_sub_f32_e32 v26, v26, v10
	global_store_dword v3, v26, s[42:43] offset:24
	v_max_f32_e32 v41, v41, v26
	v_add_f32_e32 v11, v10, v11
	v_sub_f32_e32 v27, v27, v11
	global_store_dword v3, v27, s[42:43] offset:28
	v_max_f32_e32 v41, v41, v27
	v_add_f32_e32 v12, v11, v12
	v_sub_f32_e32 v28, v28, v12
	global_store_dword v3, v28, s[42:43] offset:32
	v_max_f32_e32 v41, v41, v28
	v_add_f32_e32 v13, v12, v13
	v_sub_f32_e32 v29, v29, v13
	global_store_dword v3, v29, s[42:43] offset:36
	v_max_f32_e32 v41, v41, v29
	v_add_f32_e32 v14, v13, v14
	v_sub_f32_e32 v30, v30, v14
	global_store_dword v3, v30, s[42:43] offset:40
	v_max_f32_e32 v41, v41, v30
	v_add_f32_e32 v15, v14, v15
	v_sub_f32_e32 v31, v31, v15
	global_store_dword v3, v31, s[42:43] offset:44
	v_max_f32_e32 v41, v41, v31
	v_add_f32_e32 v16, v15, v16
	v_sub_f32_e32 v32, v32, v16
	global_store_dword v3, v32, s[42:43] offset:48
	v_max_f32_e32 v41, v41, v32
	v_add_f32_e32 v17, v16, v17
	v_sub_f32_e32 v33, v33, v17
	global_store_dword v3, v33, s[42:43] offset:52
	v_max_f32_e32 v41, v41, v33
	v_add_f32_e32 v18, v17, v18
	v_sub_f32_e32 v34, v34, v18
	global_store_dword v3, v34, s[42:43] offset:56
	v_max_f32_e32 v41, v41, v34
	v_add_f32_e32 v19, v18, v19
	v_sub_f32_e32 v35, v35, v19
	global_store_dword v3, v35, s[42:43] offset:60
	v_max_f32_e32 v41, v41, v35
	v_mov_b32_e32 v36, v41
	v_subrev_u32_e32 v38, 1, v1
	v_lshlrev_b32_e32 v38, 2, v38
	ds_bpermute_b32 v37, v38, v36
	v_cmp_le_u32_e32 vcc, 1, v1
	s_waitcnt lgkmcnt(0)
	v_max_f32_e32 v37, v36, v37
	s_nop 0
	v_cndmask_b32_e32 v36, v36, v37, vcc
	v_subrev_u32_e32 v38, 2, v1
	v_lshlrev_b32_e32 v38, 2, v38
	ds_bpermute_b32 v37, v38, v36
	v_cmp_le_u32_e32 vcc, 2, v1
	s_waitcnt lgkmcnt(0)
	v_max_f32_e32 v37, v36, v37
	s_nop 0
	v_cndmask_b32_e32 v36, v36, v37, vcc
	v_subrev_u32_e32 v38, 4, v1
	v_lshlrev_b32_e32 v38, 2, v38
	ds_bpermute_b32 v37, v38, v36
	v_cmp_le_u32_e32 vcc, 4, v1
	s_waitcnt lgkmcnt(0)
	v_max_f32_e32 v37, v36, v37
	s_nop 0
	v_cndmask_b32_e32 v36, v36, v37, vcc
	v_subrev_u32_e32 v38, 8, v1
	v_lshlrev_b32_e32 v38, 2, v38
	ds_bpermute_b32 v37, v38, v36
	v_cmp_le_u32_e32 vcc, 8, v1
	s_waitcnt lgkmcnt(0)
	v_max_f32_e32 v37, v36, v37
	s_nop 0
	v_cndmask_b32_e32 v36, v36, v37, vcc
	v_subrev_u32_e32 v38, 16, v1
	v_lshlrev_b32_e32 v38, 2, v38
	ds_bpermute_b32 v37, v38, v36
	v_cmp_le_u32_e32 vcc, 16, v1
	s_waitcnt lgkmcnt(0)
	v_max_f32_e32 v37, v36, v37
	s_nop 0
	v_cndmask_b32_e32 v36, v36, v37, vcc
	v_subrev_u32_e32 v38, 32, v1
	v_lshlrev_b32_e32 v38, 2, v38
	ds_bpermute_b32 v37, v38, v36
	v_cmp_le_u32_e32 vcc, 32, v1
	s_waitcnt lgkmcnt(0)
	v_max_f32_e32 v37, v36, v37
	s_nop 0
	v_cndmask_b32_e32 v36, v36, v37, vcc
	v_subrev_u32_e32 v38, 1, v1
	v_lshlrev_b32_e32 v38, 2, v38
	ds_bpermute_b32 v37, v38, v36
	v_mov_b32_e32 v42, s9
	v_cmp_eq_u32_e32 vcc, 0, v1
	s_waitcnt lgkmcnt(0)
	v_max_f32_e32 v37, v42, v37
	s_nop 0
	v_cndmask_b32_e32 v41, v37, v42, vcc
	v_max_f32_e32 v41, v41, v20
	global_store_dword v3, v41, s[44:45] offset:0
	v_sub_f32_e64 v43, -v4, v41
	v_mul_f32_e32 v43, 0x3fb8aa3b, v43
	v_exp_f32_e32 v43, v43
	s_nop 0
	global_store_dword v3, v43, s[46:47] offset:0
	v_max_f32_e32 v41, v41, v21
	global_store_dword v3, v41, s[44:45] offset:4
	v_sub_f32_e64 v43, -v5, v41
	v_mul_f32_e32 v43, 0x3fb8aa3b, v43
	v_exp_f32_e32 v43, v43
	s_nop 0
	global_store_dword v3, v43, s[46:47] offset:4
	v_max_f32_e32 v41, v41, v22
	global_store_dword v3, v41, s[44:45] offset:8
	v_sub_f32_e64 v43, -v6, v41
	v_mul_f32_e32 v43, 0x3fb8aa3b, v43
	v_exp_f32_e32 v43, v43
	s_nop 0
	global_store_dword v3, v43, s[46:47] offset:8
	v_max_f32_e32 v41, v41, v23
	global_store_dword v3, v41, s[44:45] offset:12
	v_sub_f32_e64 v43, -v7, v41
	v_mul_f32_e32 v43, 0x3fb8aa3b, v43
	v_exp_f32_e32 v43, v43
	s_nop 0
	global_store_dword v3, v43, s[46:47] offset:12
	v_max_f32_e32 v41, v41, v24
	global_store_dword v3, v41, s[44:45] offset:16
	v_sub_f32_e64 v43, -v8, v41
	v_mul_f32_e32 v43, 0x3fb8aa3b, v43
	v_exp_f32_e32 v43, v43
	s_nop 0
	global_store_dword v3, v43, s[46:47] offset:16
	v_max_f32_e32 v41, v41, v25
	global_store_dword v3, v41, s[44:45] offset:20
	v_sub_f32_e64 v43, -v9, v41
	v_mul_f32_e32 v43, 0x3fb8aa3b, v43
	v_exp_f32_e32 v43, v43
	s_nop 0
	global_store_dword v3, v43, s[46:47] offset:20
	v_max_f32_e32 v41, v41, v26
	global_store_dword v3, v41, s[44:45] offset:24
	v_sub_f32_e64 v43, -v10, v41
	v_mul_f32_e32 v43, 0x3fb8aa3b, v43
	v_exp_f32_e32 v43, v43
	s_nop 0
	global_store_dword v3, v43, s[46:47] offset:24
	v_max_f32_e32 v41, v41, v27
	global_store_dword v3, v41, s[44:45] offset:28
	v_sub_f32_e64 v43, -v11, v41
	v_mul_f32_e32 v43, 0x3fb8aa3b, v43
	v_exp_f32_e32 v43, v43
	s_nop 0
	global_store_dword v3, v43, s[46:47] offset:28
	v_max_f32_e32 v41, v41, v28
	global_store_dword v3, v41, s[44:45] offset:32
	v_sub_f32_e64 v43, -v12, v41
	v_mul_f32_e32 v43, 0x3fb8aa3b, v43
	v_exp_f32_e32 v43, v43
	s_nop 0
	global_store_dword v3, v43, s[46:47] offset:32
	v_max_f32_e32 v41, v41, v29
	global_store_dword v3, v41, s[44:45] offset:36
	v_sub_f32_e64 v43, -v13, v41
	v_mul_f32_e32 v43, 0x3fb8aa3b, v43
	v_exp_f32_e32 v43, v43
	s_nop 0
	global_store_dword v3, v43, s[46:47] offset:36
	v_max_f32_e32 v41, v41, v30
	global_store_dword v3, v41, s[44:45] offset:40
	v_sub_f32_e64 v43, -v14, v41
	v_mul_f32_e32 v43, 0x3fb8aa3b, v43
	v_exp_f32_e32 v43, v43
	s_nop 0
	global_store_dword v3, v43, s[46:47] offset:40
	v_max_f32_e32 v41, v41, v31
	global_store_dword v3, v41, s[44:45] offset:44
	v_sub_f32_e64 v43, -v15, v41
	v_mul_f32_e32 v43, 0x3fb8aa3b, v43
	v_exp_f32_e32 v43, v43
	s_nop 0
	global_store_dword v3, v43, s[46:47] offset:44
	v_max_f32_e32 v41, v41, v32
	global_store_dword v3, v41, s[44:45] offset:48
	v_sub_f32_e64 v43, -v16, v41
	v_mul_f32_e32 v43, 0x3fb8aa3b, v43
	v_exp_f32_e32 v43, v43
	s_nop 0
	global_store_dword v3, v43, s[46:47] offset:48
	v_max_f32_e32 v41, v41, v33
	global_store_dword v3, v41, s[44:45] offset:52
	v_sub_f32_e64 v43, -v17, v41
	v_mul_f32_e32 v43, 0x3fb8aa3b, v43
	v_exp_f32_e32 v43, v43
	s_nop 0
	global_store_dword v3, v43, s[46:47] offset:52
	v_max_f32_e32 v41, v41, v34
	global_store_dword v3, v41, s[44:45] offset:56
	v_sub_f32_e64 v43, -v18, v41
	v_mul_f32_e32 v43, 0x3fb8aa3b, v43
	v_exp_f32_e32 v43, v43
	s_nop 0
	global_store_dword v3, v43, s[46:47] offset:56
	v_max_f32_e32 v41, v41, v35
	global_store_dword v3, v41, s[44:45] offset:60
	v_sub_f32_e64 v43, -v19, v41
	v_mul_f32_e32 v43, 0x3fb8aa3b, v43
	v_exp_f32_e32 v43, v43
	s_nop 0
	global_store_dword v3, v43, s[46:47] offset:60
	s_branch .LBB0_464
.Lscan_e16_d1:
	v_mul_u32_u24_e32 v0, 16, v1
	s_add_i32 s7, s7, 1023
	v_sub_u32_e32 v0, s7, v0
	v_lshlrev_b32_e32 v2, 6, v0
	v_add_u32_e32 v2, s11, v2
	v_lshlrev_b32_e32 v3, 2, v0
	v_add_u32_e32 v3, s10, v3
	global_load_dword v4, v2, s[20:21] offset:16
	global_load_dword v20, v2, s[20:21] offset:0
	global_load_dword v5, v2, s[20:21] offset:-48
	global_load_dword v21, v2, s[20:21] offset:-64
	global_load_dword v6, v2, s[20:21] offset:-112
	global_load_dword v22, v2, s[20:21] offset:-128
	global_load_dword v7, v2, s[20:21] offset:-176
	global_load_dword v23, v2, s[20:21] offset:-192
	global_load_dword v8, v2, s[20:21] offset:-240
	global_load_dword v24, v2, s[20:21] offset:-256
	global_load_dword v9, v2, s[20:21] offset:-304
	global_load_dword v25, v2, s[20:21] offset:-320
	global_load_dword v10, v2, s[20:21] offset:-368
	global_load_dword v26, v2, s[20:21] offset:-384
	global_load_dword v11, v2, s[20:21] offset:-432
	global_load_dword v27, v2, s[20:21] offset:-448
	global_load_dword v12, v2, s[20:21] offset:-496
	global_load_dword v28, v2, s[20:21] offset:-512
	global_load_dword v13, v2, s[20:21] offset:-560
	global_load_dword v29, v2, s[20:21] offset:-576
	global_load_dword v14, v2, s[20:21] offset:-624
	global_load_dword v30, v2, s[20:21] offset:-640
	global_load_dword v15, v2, s[20:21] offset:-688
	global_load_dword v31, v2, s[20:21] offset:-704
	global_load_dword v16, v2, s[20:21] offset:-752
	global_load_dword v32, v2, s[20:21] offset:-768
	global_load_dword v17, v2, s[20:21] offset:-816
	global_load_dword v33, v2, s[20:21] offset:-832
	global_load_dword v18, v2, s[20:21] offset:-880
	global_load_dword v34, v2, s[20:21] offset:-896
	global_load_dword v19, v2, s[20:21] offset:-944
	global_load_dword v35, v2, s[20:21] offset:-960
	s_waitcnt vmcnt(0) lgkmcnt(0)
	v_add_f32_e32 v39, 0, v4
	v_add_f32_e32 v39, v39, v5
	v_add_f32_e32 v39, v39, v6
	v_add_f32_e32 v39, v39, v7
	v_add_f32_e32 v39, v39, v8
	v_add_f32_e32 v39, v39, v9
	v_add_f32_e32 v39, v39, v10
	v_add_f32_e32 v39, v39, v11
	v_add_f32_e32 v39, v39, v12
	v_add_f32_e32 v39, v39, v13
	v_add_f32_e32 v39, v39, v14
	v_add_f32_e32 v39, v39, v15
	v_add_f32_e32 v39, v39, v16
	v_add_f32_e32 v39, v39, v17
	v_add_f32_e32 v39, v39, v18
	v_add_f32_e32 v39, v39, v19
	v_mov_b32_e32 v36, v39
	v_subrev_u32_e32 v38, 1, v1
	v_lshlrev_b32_e32 v38, 2, v38
	ds_bpermute_b32 v37, v38, v36
	v_cmp_le_u32_e32 vcc, 1, v1
	s_waitcnt lgkmcnt(0)
	v_add_f32_e32 v37, v36, v37
	s_nop 0
	v_cndmask_b32_e32 v36, v36, v37, vcc
	v_subrev_u32_e32 v38, 2, v1
	v_lshlrev_b32_e32 v38, 2, v38
	ds_bpermute_b32 v37, v38, v36
	v_cmp_le_u32_e32 vcc, 2, v1
	s_waitcnt lgkmcnt(0)
	v_add_f32_e32 v37, v36, v37
	s_nop 0
	v_cndmask_b32_e32 v36, v36, v37, vcc
	v_subrev_u32_e32 v38, 4, v1
	v_lshlrev_b32_e32 v38, 2, v38
	ds_bpermute_b32 v37, v38, v36
	v_cmp_le_u32_e32 vcc, 4, v1
	s_waitcnt lgkmcnt(0)
	v_add_f32_e32 v37, v36, v37
	s_nop 0
	v_cndmask_b32_e32 v36, v36, v37, vcc
	v_subrev_u32_e32 v38, 8, v1
	v_lshlrev_b32_e32 v38, 2, v38
	ds_bpermute_b32 v37, v38, v36
	v_cmp_le_u32_e32 vcc, 8, v1
	s_waitcnt lgkmcnt(0)
	v_add_f32_e32 v37, v36, v37
	s_nop 0
	v_cndmask_b32_e32 v36, v36, v37, vcc
	v_subrev_u32_e32 v38, 16, v1
	v_lshlrev_b32_e32 v38, 2, v38
	ds_bpermute_b32 v37, v38, v36
	v_cmp_le_u32_e32 vcc, 16, v1
	s_waitcnt lgkmcnt(0)
	v_add_f32_e32 v37, v36, v37
	s_nop 0
	v_cndmask_b32_e32 v36, v36, v37, vcc
	v_subrev_u32_e32 v38, 32, v1
	v_lshlrev_b32_e32 v38, 2, v38
	ds_bpermute_b32 v37, v38, v36
	v_cmp_le_u32_e32 vcc, 32, v1
	s_waitcnt lgkmcnt(0)
	v_add_f32_e32 v37, v36, v37
	s_nop 0
	v_cndmask_b32_e32 v36, v36, v37, vcc
	v_sub_f32_e32 v40, v36, v39
	v_mov_b32_e32 v41, 0xff61b1e6
	v_add_f32_e32 v4, v40, v4
	v_sub_f32_e32 v20, v20, v4
	global_store_dword v3, v20, s[42:43] offset:0
	v_max_f32_e32 v41, v41, v20
	v_add_f32_e32 v5, v4, v5
	v_sub_f32_e32 v21, v21, v5
	global_store_dword v3, v21, s[42:43] offset:-4
	v_max_f32_e32 v41, v41, v21
	v_add_f32_e32 v6, v5, v6
	v_sub_f32_e32 v22, v22, v6
	global_store_dword v3, v22, s[42:43] offset:-8
	v_max_f32_e32 v41, v41, v22
	v_add_f32_e32 v7, v6, v7
	v_sub_f32_e32 v23, v23, v7
	global_store_dword v3, v23, s[42:43] offset:-12
	v_max_f32_e32 v41, v41, v23
	v_add_f32_e32 v8, v7, v8
	v_sub_f32_e32 v24, v24, v8
	global_store_dword v3, v24, s[42:43] offset:-16
	v_max_f32_e32 v41, v41, v24
	v_add_f32_e32 v9, v8, v9
	v_sub_f32_e32 v25, v25, v9
	global_store_dword v3, v25, s[42:43] offset:-20
	v_max_f32_e32 v41, v41, v25
	v_add_f32_e32 v10, v9, v10
	v_sub_f32_e32 v26, v26, v10
	global_store_dword v3, v26, s[42:43] offset:-24
	v_max_f32_e32 v41, v41, v26
	v_add_f32_e32 v11, v10, v11
	v_sub_f32_e32 v27, v27, v11
	global_store_dword v3, v27, s[42:43] offset:-28
	v_max_f32_e32 v41, v41, v27
	v_add_f32_e32 v12, v11, v12
	v_sub_f32_e32 v28, v28, v12
	global_store_dword v3, v28, s[42:43] offset:-32
	v_max_f32_e32 v41, v41, v28
	v_add_f32_e32 v13, v12, v13
	v_sub_f32_e32 v29, v29, v13
	global_store_dword v3, v29, s[42:43] offset:-36
	v_max_f32_e32 v41, v41, v29
	v_add_f32_e32 v14, v13, v14
	v_sub_f32_e32 v30, v30, v14
	global_store_dword v3, v30, s[42:43] offset:-40
	v_max_f32_e32 v41, v41, v30
	v_add_f32_e32 v15, v14, v15
	v_sub_f32_e32 v31, v31, v15
	global_store_dword v3, v31, s[42:43] offset:-44
	v_max_f32_e32 v41, v41, v31
	v_add_f32_e32 v16, v15, v16
	v_sub_f32_e32 v32, v32, v16
	global_store_dword v3, v32, s[42:43] offset:-48
	v_max_f32_e32 v41, v41, v32
	v_add_f32_e32 v17, v16, v17
	v_sub_f32_e32 v33, v33, v17
	global_store_dword v3, v33, s[42:43] offset:-52
	v_max_f32_e32 v41, v41, v33
	v_add_f32_e32 v18, v17, v18
	v_sub_f32_e32 v34, v34, v18
	global_store_dword v3, v34, s[42:43] offset:-56
	v_max_f32_e32 v41, v41, v34
	v_add_f32_e32 v19, v18, v19
	v_sub_f32_e32 v35, v35, v19
	global_store_dword v3, v35, s[42:43] offset:-60
	v_max_f32_e32 v41, v41, v35
	v_mov_b32_e32 v36, v41
	v_subrev_u32_e32 v38, 1, v1
	v_lshlrev_b32_e32 v38, 2, v38
	ds_bpermute_b32 v37, v38, v36
	v_cmp_le_u32_e32 vcc, 1, v1
	s_waitcnt lgkmcnt(0)
	v_max_f32_e32 v37, v36, v37
	s_nop 0
	v_cndmask_b32_e32 v36, v36, v37, vcc
	v_subrev_u32_e32 v38, 2, v1
	v_lshlrev_b32_e32 v38, 2, v38
	ds_bpermute_b32 v37, v38, v36
	v_cmp_le_u32_e32 vcc, 2, v1
	s_waitcnt lgkmcnt(0)
	v_max_f32_e32 v37, v36, v37
	s_nop 0
	v_cndmask_b32_e32 v36, v36, v37, vcc
	v_subrev_u32_e32 v38, 4, v1
	v_lshlrev_b32_e32 v38, 2, v38
	ds_bpermute_b32 v37, v38, v36
	v_cmp_le_u32_e32 vcc, 4, v1
	s_waitcnt lgkmcnt(0)
	v_max_f32_e32 v37, v36, v37
	s_nop 0
	v_cndmask_b32_e32 v36, v36, v37, vcc
	v_subrev_u32_e32 v38, 8, v1
	v_lshlrev_b32_e32 v38, 2, v38
	ds_bpermute_b32 v37, v38, v36
	v_cmp_le_u32_e32 vcc, 8, v1
	s_waitcnt lgkmcnt(0)
	v_max_f32_e32 v37, v36, v37
	s_nop 0
	v_cndmask_b32_e32 v36, v36, v37, vcc
	v_subrev_u32_e32 v38, 16, v1
	v_lshlrev_b32_e32 v38, 2, v38
	ds_bpermute_b32 v37, v38, v36
	v_cmp_le_u32_e32 vcc, 16, v1
	s_waitcnt lgkmcnt(0)
	v_max_f32_e32 v37, v36, v37
	s_nop 0
	v_cndmask_b32_e32 v36, v36, v37, vcc
	v_subrev_u32_e32 v38, 32, v1
	v_lshlrev_b32_e32 v38, 2, v38
	ds_bpermute_b32 v37, v38, v36
	v_cmp_le_u32_e32 vcc, 32, v1
	s_waitcnt lgkmcnt(0)
	v_max_f32_e32 v37, v36, v37
	s_nop 0
	v_cndmask_b32_e32 v36, v36, v37, vcc
	v_subrev_u32_e32 v38, 1, v1
	v_lshlrev_b32_e32 v38, 2, v38
	ds_bpermute_b32 v37, v38, v36
	v_mov_b32_e32 v42, s9
	v_cmp_eq_u32_e32 vcc, 0, v1
	s_waitcnt lgkmcnt(0)
	v_max_f32_e32 v37, v42, v37
	s_nop 0
	v_cndmask_b32_e32 v41, v37, v42, vcc
	v_max_f32_e32 v41, v41, v20
	global_store_dword v3, v41, s[44:45] offset:0
	v_sub_f32_e64 v43, -v4, v41
	v_mul_f32_e32 v43, 0x3fb8aa3b, v43
	v_exp_f32_e32 v43, v43
	s_nop 0
	global_store_dword v3, v43, s[46:47] offset:0
	v_max_f32_e32 v41, v41, v21
	global_store_dword v3, v41, s[44:45] offset:-4
	v_sub_f32_e64 v43, -v5, v41
	v_mul_f32_e32 v43, 0x3fb8aa3b, v43
	v_exp_f32_e32 v43, v43
	s_nop 0
	global_store_dword v3, v43, s[46:47] offset:-4
	v_max_f32_e32 v41, v41, v22
	global_store_dword v3, v41, s[44:45] offset:-8
	v_sub_f32_e64 v43, -v6, v41
	v_mul_f32_e32 v43, 0x3fb8aa3b, v43
	v_exp_f32_e32 v43, v43
	s_nop 0
	global_store_dword v3, v43, s[46:47] offset:-8
	v_max_f32_e32 v41, v41, v23
	global_store_dword v3, v41, s[44:45] offset:-12
	v_sub_f32_e64 v43, -v7, v41
	v_mul_f32_e32 v43, 0x3fb8aa3b, v43
	v_exp_f32_e32 v43, v43
	s_nop 0
	global_store_dword v3, v43, s[46:47] offset:-12
	v_max_f32_e32 v41, v41, v24
	global_store_dword v3, v41, s[44:45] offset:-16
	v_sub_f32_e64 v43, -v8, v41
	v_mul_f32_e32 v43, 0x3fb8aa3b, v43
	v_exp_f32_e32 v43, v43
	s_nop 0
	global_store_dword v3, v43, s[46:47] offset:-16
	v_max_f32_e32 v41, v41, v25
	global_store_dword v3, v41, s[44:45] offset:-20
	v_sub_f32_e64 v43, -v9, v41
	v_mul_f32_e32 v43, 0x3fb8aa3b, v43
	v_exp_f32_e32 v43, v43
	s_nop 0
	global_store_dword v3, v43, s[46:47] offset:-20
	v_max_f32_e32 v41, v41, v26
	global_store_dword v3, v41, s[44:45] offset:-24
	v_sub_f32_e64 v43, -v10, v41
	v_mul_f32_e32 v43, 0x3fb8aa3b, v43
	v_exp_f32_e32 v43, v43
	s_nop 0
	global_store_dword v3, v43, s[46:47] offset:-24
	v_max_f32_e32 v41, v41, v27
	global_store_dword v3, v41, s[44:45] offset:-28
	v_sub_f32_e64 v43, -v11, v41
	v_mul_f32_e32 v43, 0x3fb8aa3b, v43
	v_exp_f32_e32 v43, v43
	s_nop 0
	global_store_dword v3, v43, s[46:47] offset:-28
	v_max_f32_e32 v41, v41, v28
	global_store_dword v3, v41, s[44:45] offset:-32
	v_sub_f32_e64 v43, -v12, v41
	v_mul_f32_e32 v43, 0x3fb8aa3b, v43
	v_exp_f32_e32 v43, v43
	s_nop 0
	global_store_dword v3, v43, s[46:47] offset:-32
	v_max_f32_e32 v41, v41, v29
	global_store_dword v3, v41, s[44:45] offset:-36
	v_sub_f32_e64 v43, -v13, v41
	v_mul_f32_e32 v43, 0x3fb8aa3b, v43
	v_exp_f32_e32 v43, v43
	s_nop 0
	global_store_dword v3, v43, s[46:47] offset:-36
	v_max_f32_e32 v41, v41, v30
	global_store_dword v3, v41, s[44:45] offset:-40
	v_sub_f32_e64 v43, -v14, v41
	v_mul_f32_e32 v43, 0x3fb8aa3b, v43
	v_exp_f32_e32 v43, v43
	s_nop 0
	global_store_dword v3, v43, s[46:47] offset:-40
	v_max_f32_e32 v41, v41, v31
	global_store_dword v3, v41, s[44:45] offset:-44
	v_sub_f32_e64 v43, -v15, v41
	v_mul_f32_e32 v43, 0x3fb8aa3b, v43
	v_exp_f32_e32 v43, v43
	s_nop 0
	global_store_dword v3, v43, s[46:47] offset:-44
	v_max_f32_e32 v41, v41, v32
	global_store_dword v3, v41, s[44:45] offset:-48
	v_sub_f32_e64 v43, -v16, v41
	v_mul_f32_e32 v43, 0x3fb8aa3b, v43
	v_exp_f32_e32 v43, v43
	s_nop 0
	global_store_dword v3, v43, s[46:47] offset:-48
	v_max_f32_e32 v41, v41, v33
	global_store_dword v3, v41, s[44:45] offset:-52
	v_sub_f32_e64 v43, -v17, v41
	v_mul_f32_e32 v43, 0x3fb8aa3b, v43
	v_exp_f32_e32 v43, v43
	s_nop 0
	global_store_dword v3, v43, s[46:47] offset:-52
	v_max_f32_e32 v41, v41, v34
	global_store_dword v3, v41, s[44:45] offset:-56
	v_sub_f32_e64 v43, -v18, v41
	v_mul_f32_e32 v43, 0x3fb8aa3b, v43
	v_exp_f32_e32 v43, v43
	s_nop 0
	global_store_dword v3, v43, s[46:47] offset:-56
	v_max_f32_e32 v41, v41, v35
	global_store_dword v3, v41, s[44:45] offset:-60
	v_sub_f32_e64 v43, -v19, v41
	v_mul_f32_e32 v43, 0x3fb8aa3b, v43
	v_exp_f32_e32 v43, v43
	s_nop 0
	global_store_dword v3, v43, s[46:47] offset:-60
	s_branch .LBB0_464
